# norm tails: chunk dequeue atomic issued ahead of the loop-top drain wait (on top of gates XC hoist)
# baseline (speedup 1.0000x reference)
.LBB0_730:
	v_readlane_b32 s98, v254, 39
	v_readlane_b32 s99, v254, 40
	s_mov_b64 vcc, exec
	s_and_b64 exec, exec, s[98:99]
	v_mov_b32_e32 v252, 1
	global_atomic_add v253, v61, v252, s[58:59] sc0
	s_mov_b64 exec, vcc
	s_mov_b32 s99, 0
	s_waitcnt vmcnt(0)
	s_barrier
	s_mov_b64 s[0:1], exec
	v_readlane_b32 s6, v254, 39
	v_readlane_b32 s7, v254, 40
	s_and_b64 s[6:7], s[0:1], s[6:7]
	s_mov_b64 exec, s[6:7]
	s_cbranch_execz .LBB0_768
	s_cmp_lt_i32 s3, 0
	s_cbranch_scc1 .LBB0_735
	s_mov_b64 s[8:9], exec
	v_mbcnt_lo_u32_b32 v32, s8, 0
	v_mbcnt_hi_u32_b32 v32, s9, v32
	v_cmp_eq_u32_e32 vcc, 0, v32
	s_and_saveexec_b64 s[6:7], vcc
	s_cbranch_execz .LBB0_734
	s_lshl_b32 s68, s3, 6
	s_lshl_b64 s[14:15], s[68:69], 2
	v_readlane_b32 s3, v255, 2
	s_add_u32 s14, s3, s14
	v_readlane_b32 s3, v255, 3
	s_addc_u32 s15, s3, s15
	s_bcnt1_i32_b64 s3, s[8:9]
	v_mov_b32_e32 v32, s3
	global_atomic_add v61, v32, s[14:15]

.LBB0_735:
	s_mov_b64 s[8:9], exec
	v_mbcnt_lo_u32_b32 v32, s8, 0
	v_mbcnt_hi_u32_b32 v32, s9, v32
	v_cmp_eq_u32_e32 vcc, 0, v32
	s_and_saveexec_b64 s[6:7], vcc
	s_cbranch_execz .LBB0_737
	s_bcnt1_i32_b64 s3, s[8:9]
	v_mov_b32_e32 v33, v253

.LBB0_1354:
	v_readlane_b32 s98, v254, 39
	v_readlane_b32 s99, v254, 40
	s_mov_b64 vcc, exec
	s_and_b64 exec, exec, s[98:99]
	v_mov_b32_e32 v252, 1
	global_atomic_add v253, v43, v252, s[58:59] sc0
	s_mov_b64 exec, vcc
	s_mov_b32 s99, 0
	s_waitcnt vmcnt(0)
	s_barrier
	s_mov_b64 s[0:1], exec
	v_readlane_b32 s6, v254, 39
	v_readlane_b32 s7, v254, 40
	s_and_b64 s[6:7], s[0:1], s[6:7]
	s_mov_b64 exec, s[6:7]
	s_cbranch_execz .LBB0_1392
	s_cmp_lt_i32 s3, 0
	s_cbranch_scc1 .LBB0_1359
	s_mov_b64 s[8:9], exec
	v_mbcnt_lo_u32_b32 v42, s8, 0
	v_mbcnt_hi_u32_b32 v42, s9, v42
	v_cmp_eq_u32_e32 vcc, 0, v42
	s_and_saveexec_b64 s[6:7], vcc
	s_cbranch_execz .LBB0_1358
	s_lshl_b32 s56, s3, 6
	s_lshl_b64 s[10:11], s[56:57], 2
	v_readlane_b32 s3, v255, 2
	s_add_u32 s10, s3, s10
	v_readlane_b32 s3, v255, 3
	s_addc_u32 s11, s3, s11
	s_bcnt1_i32_b64 s3, s[8:9]
	v_mov_b32_e32 v42, s3
	global_atomic_add v43, v42, s[10:11]

.LBB0_1359:
	s_mov_b64 s[8:9], exec
	v_mbcnt_lo_u32_b32 v42, s8, 0
	v_mbcnt_hi_u32_b32 v42, s9, v42
	v_cmp_eq_u32_e32 vcc, 0, v42
	s_and_saveexec_b64 s[6:7], vcc
	s_cbranch_execz .LBB0_1361
	s_bcnt1_i32_b64 s3, s[8:9]
	v_mov_b32_e32 v44, v253

.LBB0_1967:
	v_readlane_b32 s98, v254, 39
	v_readlane_b32 s99, v254, 40
	s_mov_b64 vcc, exec
	s_and_b64 exec, exec, s[98:99]
	v_mov_b32_e32 v252, 1
	global_atomic_add v253, v43, v252, s[36:37] sc0
	s_mov_b64 exec, vcc
	s_mov_b32 s99, 0
	s_waitcnt vmcnt(0)
	s_barrier
	s_mov_b64 s[0:1], exec
	v_readlane_b32 s6, v254, 39
	v_readlane_b32 s7, v254, 40
	s_and_b64 s[6:7], s[0:1], s[6:7]
	s_mov_b64 exec, s[6:7]
	s_cbranch_execz .LBB0_2005
	s_cmp_lt_i32 s3, 0
	s_cbranch_scc1 .LBB0_1972
	s_mov_b64 s[10:11], exec
	v_mbcnt_lo_u32_b32 v42, s10, 0
	v_mbcnt_hi_u32_b32 v42, s11, v42
	v_cmp_eq_u32_e32 vcc, 0, v42
	s_and_saveexec_b64 s[6:7], vcc
	s_cbranch_execz .LBB0_1971
	s_lshl_b32 s14, s3, 6
	s_lshl_b64 s[12:13], s[14:15], 2
	v_readlane_b32 s3, v254, 47
	s_add_u32 s12, s3, s12
	v_readlane_b32 s3, v255, 2
	s_addc_u32 s13, s3, s13
	s_bcnt1_i32_b64 s3, s[10:11]
	v_mov_b32_e32 v42, s3
	global_atomic_add v43, v42, s[12:13]

.LBB0_1972:
	s_mov_b64 s[10:11], exec
	v_mbcnt_lo_u32_b32 v42, s10, 0
	v_mbcnt_hi_u32_b32 v42, s11, v42
	v_cmp_eq_u32_e32 vcc, 0, v42
	s_and_saveexec_b64 s[6:7], vcc
	s_cbranch_execz .LBB0_1974
	s_bcnt1_i32_b64 s3, s[10:11]
	v_mov_b32_e32 v44, v253

.LBB0_2395:
	v_readlane_b32 s98, v254, 39
	v_readlane_b32 s99, v254, 40
	s_mov_b64 vcc, exec
	s_and_b64 exec, exec, s[98:99]
	v_mov_b32_e32 v252, 1
	global_atomic_add v253, v23, v252, s[6:7] sc0
	s_mov_b64 exec, vcc
	s_mov_b32 s99, 0
	s_waitcnt vmcnt(0)
	s_barrier
	s_mov_b64 s[4:5], exec
	v_readlane_b32 s8, v254, 39
	v_readlane_b32 s9, v254, 40
	s_and_b64 s[8:9], s[4:5], s[8:9]
	s_mov_b64 exec, s[8:9]
	s_cbranch_execz .LBB0_2429
	s_mov_b64 s[12:13], exec
	v_mbcnt_lo_u32_b32 v22, s12, 0
	v_mbcnt_hi_u32_b32 v22, s13, v22
	v_cmp_eq_u32_e32 vcc, 0, v22
	s_and_saveexec_b64 s[8:9], vcc
	s_cbranch_execz .LBB0_2398
	s_bcnt1_i32_b64 s2, s[12:13]
	v_mov_b32_e32 v24, v253
